# grid barriers: one L1+L2 invalidate per XCD (by the XCD leader, completed before it releases its XCD); the other workgroups invalidate only their L1
# baseline (speedup 1.0000x reference)
.LBB0_113:
	s_or_b64 exec, exec, s[14:15]
	s_waitcnt lgkmcnt(0)
	buffer_inv sc0
	s_waitcnt vmcnt(0)

.LBB0_144:
	s_or_b64 exec, exec, s[10:11]
	s_mov_b64 s[6:7], exec
	v_mbcnt_lo_u32_b32 v0, s6, 0
	v_mbcnt_hi_u32_b32 v0, s7, v0
	v_cmp_eq_u32_e32 vcc, 0, v0
	s_waitcnt vmcnt(0)
	buffer_inv sc1
	s_waitcnt vmcnt(0)
	s_and_saveexec_b64 s[10:11], vcc
	s_cbranch_execz .LBB0_146
	s_bcnt1_i32_b64 s0, s[6:7]
	v_mov_b32_e32 v0, 0x2000
	v_mov_b32_e32 v1, s0
	global_atomic_add v0, v1, s[8:9] offset:1024

.LBB0_233:
	s_or_b64 exec, exec, s[10:11]
	s_mov_b64 s[6:7], exec
	v_mbcnt_lo_u32_b32 v0, s6, 0
	v_mbcnt_hi_u32_b32 v0, s7, v0
	v_cmp_eq_u32_e32 vcc, 0, v0
	s_waitcnt vmcnt(0)
	buffer_inv sc1
	s_waitcnt vmcnt(0)
	s_and_saveexec_b64 s[10:11], vcc
	s_cbranch_execz .LBB0_235
	s_bcnt1_i32_b64 s2, s[6:7]
	v_mov_b32_e32 v0, s2
	global_atomic_add v231, v0, s[8:9] offset:1024

.Linvd_gluj:
	s_waitcnt vmcnt(0)
	s_and_saveexec_b64 s[10:11], vcc
	s_cbranch_execz .LBB0_591
	s_bcnt1_i32_b64 s2, s[6:7]
	v_mov_b32_e32 v0, s2
	global_atomic_add v231, v0, s[8:9] offset:1024

.LBB0_1138:
	s_or_b64 exec, exec, s[16:17]
	s_waitcnt lgkmcnt(0)
	buffer_inv sc0
	s_waitcnt vmcnt(0)

.Linv1_b1j:
	s_waitcnt vmcnt(0)
	s_and_saveexec_b64 s[12:13], vcc
	s_cbranch_execz .LBB0_1171
	s_bcnt1_i32_b64 s2, s[6:7]
	v_mov_b32_e32 v0, s2
	global_atomic_add v231, v0, s[8:9] offset:1024

.Linvd_b2j:
	s_waitcnt vmcnt(0)
	s_and_saveexec_b64 s[12:13], vcc
	s_cbranch_execnz .LBB0_1374
	s_getpc_b64 s[98:99]
